# v104 with the sparse inner loop fully unrolled over the 8 key sub-tiles (immediate LDS offsets, no per-sub-tile address updates or loop control)
# baseline (speedup 1.0000x reference)
.LBB0_839:
	s_waitcnt lgkmcnt(14)
	v_sub_u32_e32 v0, s66, v3
	v_lshlrev_b32_e32 v0, 8, v0
	v_add_u32_e32 v0, s10, v0
	v_cmp_ge_i32_e32 vcc, v0, v2
	s_cbranch_vccnz .LBB0_823
	v_mov_b32_e32 v151, 0
	s_mov_b32 s8, 0
	v_mov_b32_e32 v0, 0
	v_mov_b32_e32 v1, v151
	v_mov_b32_e32 v2, v151
	v_mov_b32_e32 v3, v151
	v_mov_b32_e32 v4, v151
	v_mov_b32_e32 v5, v151
	v_mov_b32_e32 v6, v151
	v_mov_b32_e32 v7, v151
	v_mov_b32_e32 v8, v151
	v_mov_b32_e32 v9, v151
	v_mov_b32_e32 v10, v151
	v_mov_b32_e32 v11, v151
	v_mov_b32_e32 v12, v151
	v_mov_b32_e32 v13, v151
	v_mov_b32_e32 v14, v151
	v_mov_b32_e32 v15, v151
	v_mov_b32_e32 v16, 0
	v_mov_b32_e32 v17, v151
	v_mov_b32_e32 v18, v151
	v_mov_b32_e32 v19, v151
	v_mov_b32_e32 v20, v151
	v_mov_b32_e32 v21, v151
	v_mov_b32_e32 v22, v151
	v_mov_b32_e32 v23, v151
	v_mov_b32_e32 v24, v151
	v_mov_b32_e32 v25, v151
	v_mov_b32_e32 v26, v151
	v_mov_b32_e32 v27, v151
	v_mov_b32_e32 v28, v151
	v_mov_b32_e32 v29, v151
	v_mov_b32_e32 v30, v151
	v_mov_b32_e32 v31, v151
	v_mov_b32_e32 v32, 0
	v_mov_b32_e32 v33, v151
	v_mov_b32_e32 v34, v151
	v_mov_b32_e32 v35, v151
	v_mov_b32_e32 v36, v151
	v_mov_b32_e32 v37, v151
	v_mov_b32_e32 v38, v151
	v_mov_b32_e32 v39, v151
	v_mov_b32_e32 v40, v151
	v_mov_b32_e32 v41, v151
	v_mov_b32_e32 v42, v151
	v_mov_b32_e32 v43, v151
	v_mov_b32_e32 v44, v151
	v_mov_b32_e32 v45, v151
	v_mov_b32_e32 v46, v151
	v_mov_b32_e32 v47, v151
	v_mov_b32_e32 v48, 0
	v_mov_b32_e32 v49, v151
	v_mov_b32_e32 v50, v151
	v_mov_b32_e32 v51, v151
	v_mov_b32_e32 v52, v151
	v_mov_b32_e32 v53, v151
	v_mov_b32_e32 v54, v151
	v_mov_b32_e32 v55, v151
	v_mov_b32_e32 v56, v151
	v_mov_b32_e32 v57, v151
	v_mov_b32_e32 v58, v151
	v_mov_b32_e32 v59, v151
	v_mov_b32_e32 v60, v151
	v_mov_b32_e32 v61, v151
	v_mov_b32_e32 v62, v151
	v_mov_b32_e32 v63, v151
	v_add_u32_e32 v241, 0x10000, v192
	ds_read_b128 v[224:227], v200
	ds_read_b128 v[228:231], v199
	ds_read_b128 v[232:235], v198
	ds_read_b128 v[236:239], v197
	s_setprio 1
	s_waitcnt lgkmcnt(3)
	v_mfma_f32_32x32x16_bf16 v[64:79], v[224:227], v[112:115], 0
	ds_read_b128 v[224:227], v196
	s_waitcnt lgkmcnt(3)
	v_mfma_f32_32x32x16_bf16 v[64:79], v[228:231], v[116:119], v[64:79]
	ds_read_b128 v[228:231], v195
	s_waitcnt lgkmcnt(3)
	v_mfma_f32_32x32x16_bf16 v[64:79], v[232:235], v[120:123], v[64:79]
	ds_read_b128 v[232:235], v194
	s_waitcnt lgkmcnt(3)
	v_mfma_f32_32x32x16_bf16 v[64:79], v[236:239], v[124:127], v[64:79]
	ds_read_b128 v[236:239], v193
	ds_read_b64_tr_b16 v[208:209], v241
	ds_read_b64_tr_b16 v[210:211], v241 offset:2048
	s_waitcnt lgkmcnt(5)
	v_mfma_f32_32x32x16_bf16 v[64:79], v[224:227], v[128:131], v[64:79]
	ds_read_b64_tr_b16 v[212:213], v241 offset:256
	ds_read_b64_tr_b16 v[214:215], v241 offset:2304
	s_waitcnt lgkmcnt(6)
	v_mfma_f32_32x32x16_bf16 v[64:79], v[228:231], v[132:135], v[64:79]
	ds_read_b64_tr_b16 v[216:217], v241 offset:512
	ds_read_b64_tr_b16 v[218:219], v241 offset:2560
	s_waitcnt lgkmcnt(7)
	v_mfma_f32_32x32x16_bf16 v[64:79], v[232:235], v[136:139], v[64:79]
	ds_read_b64_tr_b16 v[220:221], v241 offset:768
	ds_read_b64_tr_b16 v[222:223], v241 offset:2816
	s_waitcnt lgkmcnt(8)
	v_mfma_f32_32x32x16_bf16 v[64:79], v[236:239], v[140:143], v[64:79]
	s_setprio 0
	s_nop 7
	s_nop 3
	v_exp_f32_e32 v224, v64
	v_exp_f32_e32 v225, v65
	v_exp_f32_e32 v226, v66
	v_exp_f32_e32 v227, v67
	v_exp_f32_e32 v228, v68
	v_exp_f32_e32 v229, v69
	v_exp_f32_e32 v230, v70
	v_exp_f32_e32 v231, v71
	v_exp_f32_e32 v232, v72
	v_exp_f32_e32 v233, v73
	v_exp_f32_e32 v234, v74
	v_exp_f32_e32 v235, v75
	v_exp_f32_e32 v236, v76
	v_exp_f32_e32 v237, v77
	v_exp_f32_e32 v238, v78
	v_exp_f32_e32 v239, v79
	v_cvt_pk_bf16_f32 v64, v224, v225
	v_cvt_pk_bf16_f32 v65, v226, v227
	v_cvt_pk_bf16_f32 v66, v228, v229
	v_cvt_pk_bf16_f32 v67, v230, v231
	v_cvt_pk_bf16_f32 v68, v232, v233
	v_cvt_pk_bf16_f32 v69, v234, v235
	v_cvt_pk_bf16_f32 v70, v236, v237
	v_cvt_pk_bf16_f32 v71, v238, v239
	s_setprio 1
	s_waitcnt lgkmcnt(6)
	v_mfma_f32_32x32x16_bf16 v[48:63], v[208:211], v[64:67], v[48:63]
	ds_read_b64_tr_b16 v[208:209], v241 offset:4096
	ds_read_b64_tr_b16 v[210:211], v241 offset:6144
	v_add_f32_e32 v240, 0, v224
	v_add_f32_e32 v240, v225, v240
	v_add_f32_e32 v240, v226, v240
	v_add_f32_e32 v240, v227, v240
	v_add_f32_e32 v240, v228, v240
	s_waitcnt lgkmcnt(6)
	v_mfma_f32_32x32x16_bf16 v[32:47], v[212:215], v[64:67], v[32:47]
	ds_read_b64_tr_b16 v[212:213], v241 offset:4352
	ds_read_b64_tr_b16 v[214:215], v241 offset:6400
	v_add_f32_e32 v240, v229, v240
	v_add_f32_e32 v240, v230, v240
	v_add_f32_e32 v240, v231, v240
	v_add_f32_e32 v240, v232, v240
	s_waitcnt lgkmcnt(6)
	v_mfma_f32_32x32x16_bf16 v[16:31], v[216:219], v[64:67], v[16:31]
	ds_read_b64_tr_b16 v[216:217], v241 offset:4608
	ds_read_b64_tr_b16 v[218:219], v241 offset:6656
	v_add_f32_e32 v240, v233, v240
	v_add_f32_e32 v240, v234, v240
	v_add_f32_e32 v240, v235, v240
	v_add_f32_e32 v240, v236, v240
	s_waitcnt lgkmcnt(6)
	v_mfma_f32_32x32x16_bf16 v[0:15], v[220:223], v[64:67], v[0:15]
	ds_read_b64_tr_b16 v[220:221], v241 offset:4864
	ds_read_b64_tr_b16 v[222:223], v241 offset:6912
	v_add_f32_e32 v240, v237, v240
	v_add_f32_e32 v240, v238, v240
	v_add_f32_e32 v240, v239, v240
	v_add_f32_e32 v151, v151, v240
	s_waitcnt lgkmcnt(6)
	v_mfma_f32_32x32x16_bf16 v[48:63], v[208:211], v[68:71], v[48:63]
	ds_read_b128 v[224:227], v200 offset:8192
	s_waitcnt lgkmcnt(5)
	v_mfma_f32_32x32x16_bf16 v[32:47], v[212:215], v[68:71], v[32:47]
	ds_read_b128 v[228:231], v199 offset:8192
	s_waitcnt lgkmcnt(4)
	v_mfma_f32_32x32x16_bf16 v[16:31], v[216:219], v[68:71], v[16:31]
	ds_read_b128 v[232:235], v198 offset:8192
	s_waitcnt lgkmcnt(3)
	v_mfma_f32_32x32x16_bf16 v[0:15], v[220:223], v[68:71], v[0:15]
	ds_read_b128 v[236:239], v197 offset:8192
	s_setprio 1
	s_waitcnt lgkmcnt(3)
	v_mfma_f32_32x32x16_bf16 v[64:79], v[224:227], v[112:115], 0
	ds_read_b128 v[224:227], v196 offset:8192
	s_waitcnt lgkmcnt(3)
	v_mfma_f32_32x32x16_bf16 v[64:79], v[228:231], v[116:119], v[64:79]
	ds_read_b128 v[228:231], v195 offset:8192
	s_waitcnt lgkmcnt(3)
	v_mfma_f32_32x32x16_bf16 v[64:79], v[232:235], v[120:123], v[64:79]
	ds_read_b128 v[232:235], v194 offset:8192
	s_waitcnt lgkmcnt(3)
	v_mfma_f32_32x32x16_bf16 v[64:79], v[236:239], v[124:127], v[64:79]
	ds_read_b128 v[236:239], v193 offset:8192
	ds_read_b64_tr_b16 v[208:209], v241 offset:8192
	ds_read_b64_tr_b16 v[210:211], v241 offset:10240
	s_waitcnt lgkmcnt(5)
	v_mfma_f32_32x32x16_bf16 v[64:79], v[224:227], v[128:131], v[64:79]
	ds_read_b64_tr_b16 v[212:213], v241 offset:8448
	ds_read_b64_tr_b16 v[214:215], v241 offset:10496
	s_waitcnt lgkmcnt(6)
	v_mfma_f32_32x32x16_bf16 v[64:79], v[228:231], v[132:135], v[64:79]
	ds_read_b64_tr_b16 v[216:217], v241 offset:8704
	ds_read_b64_tr_b16 v[218:219], v241 offset:10752
	s_waitcnt lgkmcnt(7)
	v_mfma_f32_32x32x16_bf16 v[64:79], v[232:235], v[136:139], v[64:79]
	ds_read_b64_tr_b16 v[220:221], v241 offset:8960
	ds_read_b64_tr_b16 v[222:223], v241 offset:11008
	s_waitcnt lgkmcnt(8)
	v_mfma_f32_32x32x16_bf16 v[64:79], v[236:239], v[140:143], v[64:79]
	s_setprio 0
	s_nop 7
	s_nop 3
	v_exp_f32_e32 v224, v64
	v_exp_f32_e32 v225, v65
	v_exp_f32_e32 v226, v66
	v_exp_f32_e32 v227, v67
	v_exp_f32_e32 v228, v68
	v_exp_f32_e32 v229, v69
	v_exp_f32_e32 v230, v70
	v_exp_f32_e32 v231, v71
	v_exp_f32_e32 v232, v72
	v_exp_f32_e32 v233, v73
	v_exp_f32_e32 v234, v74
	v_exp_f32_e32 v235, v75
	v_exp_f32_e32 v236, v76
	v_exp_f32_e32 v237, v77
	v_exp_f32_e32 v238, v78
	v_exp_f32_e32 v239, v79
	v_cvt_pk_bf16_f32 v64, v224, v225
	v_cvt_pk_bf16_f32 v65, v226, v227
	v_cvt_pk_bf16_f32 v66, v228, v229
	v_cvt_pk_bf16_f32 v67, v230, v231
	v_cvt_pk_bf16_f32 v68, v232, v233
	v_cvt_pk_bf16_f32 v69, v234, v235
	v_cvt_pk_bf16_f32 v70, v236, v237
	v_cvt_pk_bf16_f32 v71, v238, v239
	s_setprio 1
	s_waitcnt lgkmcnt(6)
	v_mfma_f32_32x32x16_bf16 v[48:63], v[208:211], v[64:67], v[48:63]
	ds_read_b64_tr_b16 v[208:209], v241 offset:12288
	ds_read_b64_tr_b16 v[210:211], v241 offset:14336
	v_add_f32_e32 v240, 0, v224
	v_add_f32_e32 v240, v225, v240
	v_add_f32_e32 v240, v226, v240
	v_add_f32_e32 v240, v227, v240
	v_add_f32_e32 v240, v228, v240
	s_waitcnt lgkmcnt(6)
	v_mfma_f32_32x32x16_bf16 v[32:47], v[212:215], v[64:67], v[32:47]
	ds_read_b64_tr_b16 v[212:213], v241 offset:12544
	ds_read_b64_tr_b16 v[214:215], v241 offset:14592
	v_add_f32_e32 v240, v229, v240
	v_add_f32_e32 v240, v230, v240
	v_add_f32_e32 v240, v231, v240
	v_add_f32_e32 v240, v232, v240
	s_waitcnt lgkmcnt(6)
	v_mfma_f32_32x32x16_bf16 v[16:31], v[216:219], v[64:67], v[16:31]
	ds_read_b64_tr_b16 v[216:217], v241 offset:12800
	ds_read_b64_tr_b16 v[218:219], v241 offset:14848
	v_add_f32_e32 v240, v233, v240
	v_add_f32_e32 v240, v234, v240
	v_add_f32_e32 v240, v235, v240
	v_add_f32_e32 v240, v236, v240
	s_waitcnt lgkmcnt(6)
	v_mfma_f32_32x32x16_bf16 v[0:15], v[220:223], v[64:67], v[0:15]
	ds_read_b64_tr_b16 v[220:221], v241 offset:13056
	ds_read_b64_tr_b16 v[222:223], v241 offset:15104
	v_add_f32_e32 v240, v237, v240
	v_add_f32_e32 v240, v238, v240
	v_add_f32_e32 v240, v239, v240
	v_add_f32_e32 v151, v151, v240
	s_waitcnt lgkmcnt(6)
	v_mfma_f32_32x32x16_bf16 v[48:63], v[208:211], v[68:71], v[48:63]
	ds_read_b128 v[224:227], v200 offset:16384
	s_waitcnt lgkmcnt(5)
	v_mfma_f32_32x32x16_bf16 v[32:47], v[212:215], v[68:71], v[32:47]
	ds_read_b128 v[228:231], v199 offset:16384
	s_waitcnt lgkmcnt(4)
	v_mfma_f32_32x32x16_bf16 v[16:31], v[216:219], v[68:71], v[16:31]
	ds_read_b128 v[232:235], v198 offset:16384
	s_waitcnt lgkmcnt(3)
	v_mfma_f32_32x32x16_bf16 v[0:15], v[220:223], v[68:71], v[0:15]
	ds_read_b128 v[236:239], v197 offset:16384
	s_setprio 1
	s_waitcnt lgkmcnt(3)
	v_mfma_f32_32x32x16_bf16 v[64:79], v[224:227], v[112:115], 0
	ds_read_b128 v[224:227], v196 offset:16384
	s_waitcnt lgkmcnt(3)
	v_mfma_f32_32x32x16_bf16 v[64:79], v[228:231], v[116:119], v[64:79]
	ds_read_b128 v[228:231], v195 offset:16384
	s_waitcnt lgkmcnt(3)
	v_mfma_f32_32x32x16_bf16 v[64:79], v[232:235], v[120:123], v[64:79]
	ds_read_b128 v[232:235], v194 offset:16384
	s_waitcnt lgkmcnt(3)
	v_mfma_f32_32x32x16_bf16 v[64:79], v[236:239], v[124:127], v[64:79]
	ds_read_b128 v[236:239], v193 offset:16384
	ds_read_b64_tr_b16 v[208:209], v241 offset:16384
	ds_read_b64_tr_b16 v[210:211], v241 offset:18432
	s_waitcnt lgkmcnt(5)
	v_mfma_f32_32x32x16_bf16 v[64:79], v[224:227], v[128:131], v[64:79]
	ds_read_b64_tr_b16 v[212:213], v241 offset:16640
	ds_read_b64_tr_b16 v[214:215], v241 offset:18688
	s_waitcnt lgkmcnt(6)
	v_mfma_f32_32x32x16_bf16 v[64:79], v[228:231], v[132:135], v[64:79]
	ds_read_b64_tr_b16 v[216:217], v241 offset:16896
	ds_read_b64_tr_b16 v[218:219], v241 offset:18944
	s_waitcnt lgkmcnt(7)
	v_mfma_f32_32x32x16_bf16 v[64:79], v[232:235], v[136:139], v[64:79]
	ds_read_b64_tr_b16 v[220:221], v241 offset:17152
	ds_read_b64_tr_b16 v[222:223], v241 offset:19200
	s_waitcnt lgkmcnt(8)
	v_mfma_f32_32x32x16_bf16 v[64:79], v[236:239], v[140:143], v[64:79]
	s_setprio 0
	s_nop 7
	s_nop 3
	v_exp_f32_e32 v224, v64
	v_exp_f32_e32 v225, v65
	v_exp_f32_e32 v226, v66
	v_exp_f32_e32 v227, v67
	v_exp_f32_e32 v228, v68
	v_exp_f32_e32 v229, v69
	v_exp_f32_e32 v230, v70
	v_exp_f32_e32 v231, v71
	v_exp_f32_e32 v232, v72
	v_exp_f32_e32 v233, v73
	v_exp_f32_e32 v234, v74
	v_exp_f32_e32 v235, v75
	v_exp_f32_e32 v236, v76
	v_exp_f32_e32 v237, v77
	v_exp_f32_e32 v238, v78
	v_exp_f32_e32 v239, v79
	v_cvt_pk_bf16_f32 v64, v224, v225
	v_cvt_pk_bf16_f32 v65, v226, v227
	v_cvt_pk_bf16_f32 v66, v228, v229
	v_cvt_pk_bf16_f32 v67, v230, v231
	v_cvt_pk_bf16_f32 v68, v232, v233
	v_cvt_pk_bf16_f32 v69, v234, v235
	v_cvt_pk_bf16_f32 v70, v236, v237
	v_cvt_pk_bf16_f32 v71, v238, v239
	s_setprio 1
	s_waitcnt lgkmcnt(6)
	v_mfma_f32_32x32x16_bf16 v[48:63], v[208:211], v[64:67], v[48:63]
	ds_read_b64_tr_b16 v[208:209], v241 offset:20480
	ds_read_b64_tr_b16 v[210:211], v241 offset:22528
	v_add_f32_e32 v240, 0, v224
	v_add_f32_e32 v240, v225, v240
	v_add_f32_e32 v240, v226, v240
	v_add_f32_e32 v240, v227, v240
	v_add_f32_e32 v240, v228, v240
	s_waitcnt lgkmcnt(6)
	v_mfma_f32_32x32x16_bf16 v[32:47], v[212:215], v[64:67], v[32:47]
	ds_read_b64_tr_b16 v[212:213], v241 offset:20736
	ds_read_b64_tr_b16 v[214:215], v241 offset:22784
	v_add_f32_e32 v240, v229, v240
	v_add_f32_e32 v240, v230, v240
	v_add_f32_e32 v240, v231, v240
	v_add_f32_e32 v240, v232, v240
	s_waitcnt lgkmcnt(6)
	v_mfma_f32_32x32x16_bf16 v[16:31], v[216:219], v[64:67], v[16:31]
	ds_read_b64_tr_b16 v[216:217], v241 offset:20992
	ds_read_b64_tr_b16 v[218:219], v241 offset:23040
	v_add_f32_e32 v240, v233, v240
	v_add_f32_e32 v240, v234, v240
	v_add_f32_e32 v240, v235, v240
	v_add_f32_e32 v240, v236, v240
	s_waitcnt lgkmcnt(6)
	v_mfma_f32_32x32x16_bf16 v[0:15], v[220:223], v[64:67], v[0:15]
	ds_read_b64_tr_b16 v[220:221], v241 offset:21248
	ds_read_b64_tr_b16 v[222:223], v241 offset:23296
	v_add_f32_e32 v240, v237, v240
	v_add_f32_e32 v240, v238, v240
	v_add_f32_e32 v240, v239, v240
	v_add_f32_e32 v151, v151, v240
	s_waitcnt lgkmcnt(6)
	v_mfma_f32_32x32x16_bf16 v[48:63], v[208:211], v[68:71], v[48:63]
	ds_read_b128 v[224:227], v200 offset:24576
	s_waitcnt lgkmcnt(5)
	v_mfma_f32_32x32x16_bf16 v[32:47], v[212:215], v[68:71], v[32:47]
	ds_read_b128 v[228:231], v199 offset:24576
	s_waitcnt lgkmcnt(4)
	v_mfma_f32_32x32x16_bf16 v[16:31], v[216:219], v[68:71], v[16:31]
	ds_read_b128 v[232:235], v198 offset:24576
	s_waitcnt lgkmcnt(3)
	v_mfma_f32_32x32x16_bf16 v[0:15], v[220:223], v[68:71], v[0:15]
	ds_read_b128 v[236:239], v197 offset:24576
	s_setprio 1
	s_waitcnt lgkmcnt(3)
	v_mfma_f32_32x32x16_bf16 v[64:79], v[224:227], v[112:115], 0
	ds_read_b128 v[224:227], v196 offset:24576
	s_waitcnt lgkmcnt(3)
	v_mfma_f32_32x32x16_bf16 v[64:79], v[228:231], v[116:119], v[64:79]
	ds_read_b128 v[228:231], v195 offset:24576
	s_waitcnt lgkmcnt(3)
	v_mfma_f32_32x32x16_bf16 v[64:79], v[232:235], v[120:123], v[64:79]
	ds_read_b128 v[232:235], v194 offset:24576
	s_waitcnt lgkmcnt(3)
	v_mfma_f32_32x32x16_bf16 v[64:79], v[236:239], v[124:127], v[64:79]
	ds_read_b128 v[236:239], v193 offset:24576
	ds_read_b64_tr_b16 v[208:209], v241 offset:24576
	ds_read_b64_tr_b16 v[210:211], v241 offset:26624
	s_waitcnt lgkmcnt(5)
	v_mfma_f32_32x32x16_bf16 v[64:79], v[224:227], v[128:131], v[64:79]
	ds_read_b64_tr_b16 v[212:213], v241 offset:24832
	ds_read_b64_tr_b16 v[214:215], v241 offset:26880
	s_waitcnt lgkmcnt(6)
	v_mfma_f32_32x32x16_bf16 v[64:79], v[228:231], v[132:135], v[64:79]
	ds_read_b64_tr_b16 v[216:217], v241 offset:25088
	ds_read_b64_tr_b16 v[218:219], v241 offset:27136
	s_waitcnt lgkmcnt(7)
	v_mfma_f32_32x32x16_bf16 v[64:79], v[232:235], v[136:139], v[64:79]
	ds_read_b64_tr_b16 v[220:221], v241 offset:25344
	ds_read_b64_tr_b16 v[222:223], v241 offset:27392
	s_waitcnt lgkmcnt(8)
	v_mfma_f32_32x32x16_bf16 v[64:79], v[236:239], v[140:143], v[64:79]
	s_setprio 0
	s_nop 7
	s_nop 3
	v_exp_f32_e32 v224, v64
	v_exp_f32_e32 v225, v65
	v_exp_f32_e32 v226, v66
	v_exp_f32_e32 v227, v67
	v_exp_f32_e32 v228, v68
	v_exp_f32_e32 v229, v69
	v_exp_f32_e32 v230, v70
	v_exp_f32_e32 v231, v71
	v_exp_f32_e32 v232, v72
	v_exp_f32_e32 v233, v73
	v_exp_f32_e32 v234, v74
	v_exp_f32_e32 v235, v75
	v_exp_f32_e32 v236, v76
	v_exp_f32_e32 v237, v77
	v_exp_f32_e32 v238, v78
	v_exp_f32_e32 v239, v79
	v_cvt_pk_bf16_f32 v64, v224, v225
	v_cvt_pk_bf16_f32 v65, v226, v227
	v_cvt_pk_bf16_f32 v66, v228, v229
	v_cvt_pk_bf16_f32 v67, v230, v231
	v_cvt_pk_bf16_f32 v68, v232, v233
	v_cvt_pk_bf16_f32 v69, v234, v235
	v_cvt_pk_bf16_f32 v70, v236, v237
	v_cvt_pk_bf16_f32 v71, v238, v239
	s_setprio 1
	s_waitcnt lgkmcnt(6)
	v_mfma_f32_32x32x16_bf16 v[48:63], v[208:211], v[64:67], v[48:63]
	ds_read_b64_tr_b16 v[208:209], v241 offset:28672
	ds_read_b64_tr_b16 v[210:211], v241 offset:30720
	v_add_f32_e32 v240, 0, v224
	v_add_f32_e32 v240, v225, v240
	v_add_f32_e32 v240, v226, v240
	v_add_f32_e32 v240, v227, v240
	v_add_f32_e32 v240, v228, v240
	s_waitcnt lgkmcnt(6)
	v_mfma_f32_32x32x16_bf16 v[32:47], v[212:215], v[64:67], v[32:47]
	ds_read_b64_tr_b16 v[212:213], v241 offset:28928
	ds_read_b64_tr_b16 v[214:215], v241 offset:30976
	v_add_f32_e32 v240, v229, v240
	v_add_f32_e32 v240, v230, v240
	v_add_f32_e32 v240, v231, v240
	v_add_f32_e32 v240, v232, v240
	s_waitcnt lgkmcnt(6)
	v_mfma_f32_32x32x16_bf16 v[16:31], v[216:219], v[64:67], v[16:31]
	ds_read_b64_tr_b16 v[216:217], v241 offset:29184
	ds_read_b64_tr_b16 v[218:219], v241 offset:31232
	v_add_f32_e32 v240, v233, v240
	v_add_f32_e32 v240, v234, v240
	v_add_f32_e32 v240, v235, v240
	v_add_f32_e32 v240, v236, v240
	s_waitcnt lgkmcnt(6)
	v_mfma_f32_32x32x16_bf16 v[0:15], v[220:223], v[64:67], v[0:15]
	ds_read_b64_tr_b16 v[220:221], v241 offset:29440
	ds_read_b64_tr_b16 v[222:223], v241 offset:31488
	v_add_f32_e32 v240, v237, v240
	v_add_f32_e32 v240, v238, v240
	v_add_f32_e32 v240, v239, v240
	v_add_f32_e32 v151, v151, v240
	s_waitcnt lgkmcnt(6)
	v_mfma_f32_32x32x16_bf16 v[48:63], v[208:211], v[68:71], v[48:63]
	ds_read_b128 v[224:227], v200 offset:32768
	s_waitcnt lgkmcnt(5)
	v_mfma_f32_32x32x16_bf16 v[32:47], v[212:215], v[68:71], v[32:47]
	ds_read_b128 v[228:231], v199 offset:32768
	s_waitcnt lgkmcnt(4)
	v_mfma_f32_32x32x16_bf16 v[16:31], v[216:219], v[68:71], v[16:31]
	ds_read_b128 v[232:235], v198 offset:32768
	s_waitcnt lgkmcnt(3)
	v_mfma_f32_32x32x16_bf16 v[0:15], v[220:223], v[68:71], v[0:15]
	ds_read_b128 v[236:239], v197 offset:32768
	s_setprio 1
	s_waitcnt lgkmcnt(3)
	v_mfma_f32_32x32x16_bf16 v[64:79], v[224:227], v[112:115], 0
	ds_read_b128 v[224:227], v196 offset:32768
	s_waitcnt lgkmcnt(3)
	v_mfma_f32_32x32x16_bf16 v[64:79], v[228:231], v[116:119], v[64:79]
	ds_read_b128 v[228:231], v195 offset:32768
	s_waitcnt lgkmcnt(3)
	v_mfma_f32_32x32x16_bf16 v[64:79], v[232:235], v[120:123], v[64:79]
	ds_read_b128 v[232:235], v194 offset:32768
	s_waitcnt lgkmcnt(3)
	v_mfma_f32_32x32x16_bf16 v[64:79], v[236:239], v[124:127], v[64:79]
	ds_read_b128 v[236:239], v193 offset:32768
	ds_read_b64_tr_b16 v[208:209], v241 offset:32768
	ds_read_b64_tr_b16 v[210:211], v241 offset:34816
	s_waitcnt lgkmcnt(5)
	v_mfma_f32_32x32x16_bf16 v[64:79], v[224:227], v[128:131], v[64:79]
	ds_read_b64_tr_b16 v[212:213], v241 offset:33024
	ds_read_b64_tr_b16 v[214:215], v241 offset:35072
	s_waitcnt lgkmcnt(6)
	v_mfma_f32_32x32x16_bf16 v[64:79], v[228:231], v[132:135], v[64:79]
	ds_read_b64_tr_b16 v[216:217], v241 offset:33280
	ds_read_b64_tr_b16 v[218:219], v241 offset:35328
	s_waitcnt lgkmcnt(7)
	v_mfma_f32_32x32x16_bf16 v[64:79], v[232:235], v[136:139], v[64:79]
	ds_read_b64_tr_b16 v[220:221], v241 offset:33536
	ds_read_b64_tr_b16 v[222:223], v241 offset:35584
	s_waitcnt lgkmcnt(8)
	v_mfma_f32_32x32x16_bf16 v[64:79], v[236:239], v[140:143], v[64:79]
	s_setprio 0
	s_nop 7
	s_nop 3
	v_exp_f32_e32 v224, v64
	v_exp_f32_e32 v225, v65
	v_exp_f32_e32 v226, v66
	v_exp_f32_e32 v227, v67
	v_exp_f32_e32 v228, v68
	v_exp_f32_e32 v229, v69
	v_exp_f32_e32 v230, v70
	v_exp_f32_e32 v231, v71
	v_exp_f32_e32 v232, v72
	v_exp_f32_e32 v233, v73
	v_exp_f32_e32 v234, v74
	v_exp_f32_e32 v235, v75
	v_exp_f32_e32 v236, v76
	v_exp_f32_e32 v237, v77
	v_exp_f32_e32 v238, v78
	v_exp_f32_e32 v239, v79
	v_cvt_pk_bf16_f32 v64, v224, v225
	v_cvt_pk_bf16_f32 v65, v226, v227
	v_cvt_pk_bf16_f32 v66, v228, v229
	v_cvt_pk_bf16_f32 v67, v230, v231
	v_cvt_pk_bf16_f32 v68, v232, v233
	v_cvt_pk_bf16_f32 v69, v234, v235
	v_cvt_pk_bf16_f32 v70, v236, v237
	v_cvt_pk_bf16_f32 v71, v238, v239
	s_setprio 1
	s_waitcnt lgkmcnt(6)
	v_mfma_f32_32x32x16_bf16 v[48:63], v[208:211], v[64:67], v[48:63]
	ds_read_b64_tr_b16 v[208:209], v241 offset:36864
	ds_read_b64_tr_b16 v[210:211], v241 offset:38912
	v_add_f32_e32 v240, 0, v224
	v_add_f32_e32 v240, v225, v240
	v_add_f32_e32 v240, v226, v240
	v_add_f32_e32 v240, v227, v240
	v_add_f32_e32 v240, v228, v240
	s_waitcnt lgkmcnt(6)
	v_mfma_f32_32x32x16_bf16 v[32:47], v[212:215], v[64:67], v[32:47]
	ds_read_b64_tr_b16 v[212:213], v241 offset:37120
	ds_read_b64_tr_b16 v[214:215], v241 offset:39168
	v_add_f32_e32 v240, v229, v240
	v_add_f32_e32 v240, v230, v240
	v_add_f32_e32 v240, v231, v240
	v_add_f32_e32 v240, v232, v240
	s_waitcnt lgkmcnt(6)
	v_mfma_f32_32x32x16_bf16 v[16:31], v[216:219], v[64:67], v[16:31]
	ds_read_b64_tr_b16 v[216:217], v241 offset:37376
	ds_read_b64_tr_b16 v[218:219], v241 offset:39424
	v_add_f32_e32 v240, v233, v240
	v_add_f32_e32 v240, v234, v240
	v_add_f32_e32 v240, v235, v240
	v_add_f32_e32 v240, v236, v240
	s_waitcnt lgkmcnt(6)
	v_mfma_f32_32x32x16_bf16 v[0:15], v[220:223], v[64:67], v[0:15]
	ds_read_b64_tr_b16 v[220:221], v241 offset:37632
	ds_read_b64_tr_b16 v[222:223], v241 offset:39680
	v_add_f32_e32 v240, v237, v240
	v_add_f32_e32 v240, v238, v240
	v_add_f32_e32 v240, v239, v240
	v_add_f32_e32 v151, v151, v240
	s_waitcnt lgkmcnt(6)
	v_mfma_f32_32x32x16_bf16 v[48:63], v[208:211], v[68:71], v[48:63]
	ds_read_b128 v[224:227], v200 offset:40960
	s_waitcnt lgkmcnt(5)
	v_mfma_f32_32x32x16_bf16 v[32:47], v[212:215], v[68:71], v[32:47]
	ds_read_b128 v[228:231], v199 offset:40960
	s_waitcnt lgkmcnt(4)
	v_mfma_f32_32x32x16_bf16 v[16:31], v[216:219], v[68:71], v[16:31]
	ds_read_b128 v[232:235], v198 offset:40960
	s_waitcnt lgkmcnt(3)
	v_mfma_f32_32x32x16_bf16 v[0:15], v[220:223], v[68:71], v[0:15]
	ds_read_b128 v[236:239], v197 offset:40960
	s_setprio 1
	s_waitcnt lgkmcnt(3)
	v_mfma_f32_32x32x16_bf16 v[64:79], v[224:227], v[112:115], 0
	ds_read_b128 v[224:227], v196 offset:40960
	s_waitcnt lgkmcnt(3)
	v_mfma_f32_32x32x16_bf16 v[64:79], v[228:231], v[116:119], v[64:79]
	ds_read_b128 v[228:231], v195 offset:40960
	s_waitcnt lgkmcnt(3)
	v_mfma_f32_32x32x16_bf16 v[64:79], v[232:235], v[120:123], v[64:79]
	ds_read_b128 v[232:235], v194 offset:40960
	s_waitcnt lgkmcnt(3)
	v_mfma_f32_32x32x16_bf16 v[64:79], v[236:239], v[124:127], v[64:79]
	ds_read_b128 v[236:239], v193 offset:40960
	ds_read_b64_tr_b16 v[208:209], v241 offset:40960
	ds_read_b64_tr_b16 v[210:211], v241 offset:43008
	s_waitcnt lgkmcnt(5)
	v_mfma_f32_32x32x16_bf16 v[64:79], v[224:227], v[128:131], v[64:79]
	ds_read_b64_tr_b16 v[212:213], v241 offset:41216
	ds_read_b64_tr_b16 v[214:215], v241 offset:43264
	s_waitcnt lgkmcnt(6)
	v_mfma_f32_32x32x16_bf16 v[64:79], v[228:231], v[132:135], v[64:79]
	ds_read_b64_tr_b16 v[216:217], v241 offset:41472
	ds_read_b64_tr_b16 v[218:219], v241 offset:43520
	s_waitcnt lgkmcnt(7)
	v_mfma_f32_32x32x16_bf16 v[64:79], v[232:235], v[136:139], v[64:79]
	ds_read_b64_tr_b16 v[220:221], v241 offset:41728
	ds_read_b64_tr_b16 v[222:223], v241 offset:43776
	s_waitcnt lgkmcnt(8)
	v_mfma_f32_32x32x16_bf16 v[64:79], v[236:239], v[140:143], v[64:79]
	s_setprio 0
	s_nop 7
	s_nop 3
	v_exp_f32_e32 v224, v64
	v_exp_f32_e32 v225, v65
	v_exp_f32_e32 v226, v66
	v_exp_f32_e32 v227, v67
	v_exp_f32_e32 v228, v68
	v_exp_f32_e32 v229, v69
	v_exp_f32_e32 v230, v70
	v_exp_f32_e32 v231, v71
	v_exp_f32_e32 v232, v72
	v_exp_f32_e32 v233, v73
	v_exp_f32_e32 v234, v74
	v_exp_f32_e32 v235, v75
	v_exp_f32_e32 v236, v76
	v_exp_f32_e32 v237, v77
	v_exp_f32_e32 v238, v78
	v_exp_f32_e32 v239, v79
	v_cvt_pk_bf16_f32 v64, v224, v225
	v_cvt_pk_bf16_f32 v65, v226, v227
	v_cvt_pk_bf16_f32 v66, v228, v229
	v_cvt_pk_bf16_f32 v67, v230, v231
	v_cvt_pk_bf16_f32 v68, v232, v233
	v_cvt_pk_bf16_f32 v69, v234, v235
	v_cvt_pk_bf16_f32 v70, v236, v237
	v_cvt_pk_bf16_f32 v71, v238, v239
	s_setprio 1
	s_waitcnt lgkmcnt(6)
	v_mfma_f32_32x32x16_bf16 v[48:63], v[208:211], v[64:67], v[48:63]
	ds_read_b64_tr_b16 v[208:209], v241 offset:45056
	ds_read_b64_tr_b16 v[210:211], v241 offset:47104
	v_add_f32_e32 v240, 0, v224
	v_add_f32_e32 v240, v225, v240
	v_add_f32_e32 v240, v226, v240
	v_add_f32_e32 v240, v227, v240
	v_add_f32_e32 v240, v228, v240
	s_waitcnt lgkmcnt(6)
	v_mfma_f32_32x32x16_bf16 v[32:47], v[212:215], v[64:67], v[32:47]
	ds_read_b64_tr_b16 v[212:213], v241 offset:45312
	ds_read_b64_tr_b16 v[214:215], v241 offset:47360
	v_add_f32_e32 v240, v229, v240
	v_add_f32_e32 v240, v230, v240
	v_add_f32_e32 v240, v231, v240
	v_add_f32_e32 v240, v232, v240
	s_waitcnt lgkmcnt(6)
	v_mfma_f32_32x32x16_bf16 v[16:31], v[216:219], v[64:67], v[16:31]
	ds_read_b64_tr_b16 v[216:217], v241 offset:45568
	ds_read_b64_tr_b16 v[218:219], v241 offset:47616
	v_add_f32_e32 v240, v233, v240
	v_add_f32_e32 v240, v234, v240
	v_add_f32_e32 v240, v235, v240
	v_add_f32_e32 v240, v236, v240
	s_waitcnt lgkmcnt(6)
	v_mfma_f32_32x32x16_bf16 v[0:15], v[220:223], v[64:67], v[0:15]
	ds_read_b64_tr_b16 v[220:221], v241 offset:45824
	ds_read_b64_tr_b16 v[222:223], v241 offset:47872
	v_add_f32_e32 v240, v237, v240
	v_add_f32_e32 v240, v238, v240
	v_add_f32_e32 v240, v239, v240
	v_add_f32_e32 v151, v151, v240
	s_waitcnt lgkmcnt(6)
	v_mfma_f32_32x32x16_bf16 v[48:63], v[208:211], v[68:71], v[48:63]
	ds_read_b128 v[224:227], v200 offset:49152
	s_waitcnt lgkmcnt(5)
	v_mfma_f32_32x32x16_bf16 v[32:47], v[212:215], v[68:71], v[32:47]
	ds_read_b128 v[228:231], v199 offset:49152
	s_waitcnt lgkmcnt(4)
	v_mfma_f32_32x32x16_bf16 v[16:31], v[216:219], v[68:71], v[16:31]
	ds_read_b128 v[232:235], v198 offset:49152
	s_waitcnt lgkmcnt(3)
	v_mfma_f32_32x32x16_bf16 v[0:15], v[220:223], v[68:71], v[0:15]
	ds_read_b128 v[236:239], v197 offset:49152
	s_setprio 1
	s_waitcnt lgkmcnt(3)
	v_mfma_f32_32x32x16_bf16 v[64:79], v[224:227], v[112:115], 0
	ds_read_b128 v[224:227], v196 offset:49152
	s_waitcnt lgkmcnt(3)
	v_mfma_f32_32x32x16_bf16 v[64:79], v[228:231], v[116:119], v[64:79]
	ds_read_b128 v[228:231], v195 offset:49152
	s_waitcnt lgkmcnt(3)
	v_mfma_f32_32x32x16_bf16 v[64:79], v[232:235], v[120:123], v[64:79]
	ds_read_b128 v[232:235], v194 offset:49152
	s_waitcnt lgkmcnt(3)
	v_mfma_f32_32x32x16_bf16 v[64:79], v[236:239], v[124:127], v[64:79]
	ds_read_b128 v[236:239], v193 offset:49152
	ds_read_b64_tr_b16 v[208:209], v241 offset:49152
	ds_read_b64_tr_b16 v[210:211], v241 offset:51200
	s_waitcnt lgkmcnt(5)
	v_mfma_f32_32x32x16_bf16 v[64:79], v[224:227], v[128:131], v[64:79]
	ds_read_b64_tr_b16 v[212:213], v241 offset:49408
	ds_read_b64_tr_b16 v[214:215], v241 offset:51456
	s_waitcnt lgkmcnt(6)
	v_mfma_f32_32x32x16_bf16 v[64:79], v[228:231], v[132:135], v[64:79]
	ds_read_b64_tr_b16 v[216:217], v241 offset:49664
	ds_read_b64_tr_b16 v[218:219], v241 offset:51712
	s_waitcnt lgkmcnt(7)
	v_mfma_f32_32x32x16_bf16 v[64:79], v[232:235], v[136:139], v[64:79]
	ds_read_b64_tr_b16 v[220:221], v241 offset:49920
	ds_read_b64_tr_b16 v[222:223], v241 offset:51968
	s_waitcnt lgkmcnt(8)
	v_mfma_f32_32x32x16_bf16 v[64:79], v[236:239], v[140:143], v[64:79]
	s_setprio 0
	s_nop 7
	s_nop 3
	v_exp_f32_e32 v224, v64
	v_exp_f32_e32 v225, v65
	v_exp_f32_e32 v226, v66
	v_exp_f32_e32 v227, v67
	v_exp_f32_e32 v228, v68
	v_exp_f32_e32 v229, v69
	v_exp_f32_e32 v230, v70
	v_exp_f32_e32 v231, v71
	v_exp_f32_e32 v232, v72
	v_exp_f32_e32 v233, v73
	v_exp_f32_e32 v234, v74
	v_exp_f32_e32 v235, v75
	v_exp_f32_e32 v236, v76
	v_exp_f32_e32 v237, v77
	v_exp_f32_e32 v238, v78
	v_exp_f32_e32 v239, v79
	v_cvt_pk_bf16_f32 v64, v224, v225
	v_cvt_pk_bf16_f32 v65, v226, v227
	v_cvt_pk_bf16_f32 v66, v228, v229
	v_cvt_pk_bf16_f32 v67, v230, v231
	v_cvt_pk_bf16_f32 v68, v232, v233
	v_cvt_pk_bf16_f32 v69, v234, v235
	v_cvt_pk_bf16_f32 v70, v236, v237
	v_cvt_pk_bf16_f32 v71, v238, v239
	s_setprio 1
	s_waitcnt lgkmcnt(6)
	v_mfma_f32_32x32x16_bf16 v[48:63], v[208:211], v[64:67], v[48:63]
	ds_read_b64_tr_b16 v[208:209], v241 offset:53248
	ds_read_b64_tr_b16 v[210:211], v241 offset:55296
	v_add_f32_e32 v240, 0, v224
	v_add_f32_e32 v240, v225, v240
	v_add_f32_e32 v240, v226, v240
	v_add_f32_e32 v240, v227, v240
	v_add_f32_e32 v240, v228, v240
	s_waitcnt lgkmcnt(6)
	v_mfma_f32_32x32x16_bf16 v[32:47], v[212:215], v[64:67], v[32:47]
	ds_read_b64_tr_b16 v[212:213], v241 offset:53504
	ds_read_b64_tr_b16 v[214:215], v241 offset:55552
	v_add_f32_e32 v240, v229, v240
	v_add_f32_e32 v240, v230, v240
	v_add_f32_e32 v240, v231, v240
	v_add_f32_e32 v240, v232, v240
	s_waitcnt lgkmcnt(6)
	v_mfma_f32_32x32x16_bf16 v[16:31], v[216:219], v[64:67], v[16:31]
	ds_read_b64_tr_b16 v[216:217], v241 offset:53760
	ds_read_b64_tr_b16 v[218:219], v241 offset:55808
	v_add_f32_e32 v240, v233, v240
	v_add_f32_e32 v240, v234, v240
	v_add_f32_e32 v240, v235, v240
	v_add_f32_e32 v240, v236, v240
	s_waitcnt lgkmcnt(6)
	v_mfma_f32_32x32x16_bf16 v[0:15], v[220:223], v[64:67], v[0:15]
	ds_read_b64_tr_b16 v[220:221], v241 offset:54016
	ds_read_b64_tr_b16 v[222:223], v241 offset:56064
	v_add_f32_e32 v240, v237, v240
	v_add_f32_e32 v240, v238, v240
	v_add_f32_e32 v240, v239, v240
	v_add_f32_e32 v151, v151, v240
	s_waitcnt lgkmcnt(6)
	v_mfma_f32_32x32x16_bf16 v[48:63], v[208:211], v[68:71], v[48:63]
	ds_read_b128 v[224:227], v200 offset:57344
	s_waitcnt lgkmcnt(5)
	v_mfma_f32_32x32x16_bf16 v[32:47], v[212:215], v[68:71], v[32:47]
	ds_read_b128 v[228:231], v199 offset:57344
	s_waitcnt lgkmcnt(4)
	v_mfma_f32_32x32x16_bf16 v[16:31], v[216:219], v[68:71], v[16:31]
	ds_read_b128 v[232:235], v198 offset:57344
	s_waitcnt lgkmcnt(3)
	v_mfma_f32_32x32x16_bf16 v[0:15], v[220:223], v[68:71], v[0:15]
	ds_read_b128 v[236:239], v197 offset:57344
	s_setprio 1
	s_waitcnt lgkmcnt(3)
	v_mfma_f32_32x32x16_bf16 v[64:79], v[224:227], v[112:115], 0
	ds_read_b128 v[224:227], v196 offset:57344
	s_waitcnt lgkmcnt(3)
	v_mfma_f32_32x32x16_bf16 v[64:79], v[228:231], v[116:119], v[64:79]
	ds_read_b128 v[228:231], v195 offset:57344
	s_waitcnt lgkmcnt(3)
	v_mfma_f32_32x32x16_bf16 v[64:79], v[232:235], v[120:123], v[64:79]
	ds_read_b128 v[232:235], v194 offset:57344
	s_waitcnt lgkmcnt(3)
	v_mfma_f32_32x32x16_bf16 v[64:79], v[236:239], v[124:127], v[64:79]
	ds_read_b128 v[236:239], v193 offset:57344
	ds_read_b64_tr_b16 v[208:209], v241 offset:57344
	ds_read_b64_tr_b16 v[210:211], v241 offset:59392
	s_waitcnt lgkmcnt(5)
	v_mfma_f32_32x32x16_bf16 v[64:79], v[224:227], v[128:131], v[64:79]
	ds_read_b64_tr_b16 v[212:213], v241 offset:57600
	ds_read_b64_tr_b16 v[214:215], v241 offset:59648
	s_waitcnt lgkmcnt(6)
	v_mfma_f32_32x32x16_bf16 v[64:79], v[228:231], v[132:135], v[64:79]
	ds_read_b64_tr_b16 v[216:217], v241 offset:57856
	ds_read_b64_tr_b16 v[218:219], v241 offset:59904
	s_waitcnt lgkmcnt(7)
	v_mfma_f32_32x32x16_bf16 v[64:79], v[232:235], v[136:139], v[64:79]
	ds_read_b64_tr_b16 v[220:221], v241 offset:58112
	ds_read_b64_tr_b16 v[222:223], v241 offset:60160
	s_waitcnt lgkmcnt(8)
	v_mfma_f32_32x32x16_bf16 v[64:79], v[236:239], v[140:143], v[64:79]
	s_setprio 0
	s_nop 7
	s_nop 3
	v_exp_f32_e32 v224, v64
	v_exp_f32_e32 v225, v65
	v_exp_f32_e32 v226, v66
	v_exp_f32_e32 v227, v67
	v_exp_f32_e32 v228, v68
	v_exp_f32_e32 v229, v69
	v_exp_f32_e32 v230, v70
	v_exp_f32_e32 v231, v71
	v_exp_f32_e32 v232, v72
	v_exp_f32_e32 v233, v73
	v_exp_f32_e32 v234, v74
	v_exp_f32_e32 v235, v75
	v_exp_f32_e32 v236, v76
	v_exp_f32_e32 v237, v77
	v_exp_f32_e32 v238, v78
	v_exp_f32_e32 v239, v79
	v_cvt_pk_bf16_f32 v64, v224, v225
	v_cvt_pk_bf16_f32 v65, v226, v227
	v_cvt_pk_bf16_f32 v66, v228, v229
	v_cvt_pk_bf16_f32 v67, v230, v231
	v_cvt_pk_bf16_f32 v68, v232, v233
	v_cvt_pk_bf16_f32 v69, v234, v235
	v_cvt_pk_bf16_f32 v70, v236, v237
	v_cvt_pk_bf16_f32 v71, v238, v239
	s_setprio 1
	s_waitcnt lgkmcnt(6)
	v_mfma_f32_32x32x16_bf16 v[48:63], v[208:211], v[64:67], v[48:63]
	ds_read_b64_tr_b16 v[208:209], v241 offset:61440
	ds_read_b64_tr_b16 v[210:211], v241 offset:63488
	v_add_f32_e32 v240, 0, v224
	v_add_f32_e32 v240, v225, v240
	v_add_f32_e32 v240, v226, v240
	v_add_f32_e32 v240, v227, v240
	v_add_f32_e32 v240, v228, v240
	s_waitcnt lgkmcnt(6)
	v_mfma_f32_32x32x16_bf16 v[32:47], v[212:215], v[64:67], v[32:47]
	ds_read_b64_tr_b16 v[212:213], v241 offset:61696
	ds_read_b64_tr_b16 v[214:215], v241 offset:63744
	v_add_f32_e32 v240, v229, v240
	v_add_f32_e32 v240, v230, v240
	v_add_f32_e32 v240, v231, v240
	v_add_f32_e32 v240, v232, v240
	s_waitcnt lgkmcnt(6)
	v_mfma_f32_32x32x16_bf16 v[16:31], v[216:219], v[64:67], v[16:31]
	ds_read_b64_tr_b16 v[216:217], v241 offset:61952
	ds_read_b64_tr_b16 v[218:219], v241 offset:64000
	v_add_f32_e32 v240, v233, v240
	v_add_f32_e32 v240, v234, v240
	v_add_f32_e32 v240, v235, v240
	v_add_f32_e32 v240, v236, v240
	s_waitcnt lgkmcnt(6)
	v_mfma_f32_32x32x16_bf16 v[0:15], v[220:223], v[64:67], v[0:15]
	ds_read_b64_tr_b16 v[220:221], v241 offset:62208
	ds_read_b64_tr_b16 v[222:223], v241 offset:64256
	v_add_f32_e32 v240, v237, v240
	v_add_f32_e32 v240, v238, v240
	v_add_f32_e32 v240, v239, v240
	v_add_f32_e32 v151, v151, v240
	s_waitcnt lgkmcnt(6)
	v_mfma_f32_32x32x16_bf16 v[48:63], v[208:211], v[68:71], v[48:63]
	s_waitcnt lgkmcnt(4)
	v_mfma_f32_32x32x16_bf16 v[32:47], v[212:215], v[68:71], v[32:47]
	s_waitcnt lgkmcnt(2)
	v_mfma_f32_32x32x16_bf16 v[16:31], v[216:219], v[68:71], v[16:31]
	s_waitcnt lgkmcnt(0)
	v_mfma_f32_32x32x16_bf16 v[0:15], v[220:223], v[68:71], v[0:15]
	s_waitcnt lgkmcnt(0)
	s_setprio 0
	ds_bpermute_b32 v66, v191, v151
	v_lshrrev_b32_e32 v65, 2, v207
	v_cmp_ne_u32_e32 vcc, -1, v207
	v_and_b32_e32 v64, 3, v207
	v_lshl_add_u32 v65, s68, 13, v65
	v_mad_u64_u32 v[64:65], s[8:9], v65, 3, v[64:65]
	s_and_b64 s[30:31], vcc, s[4:5]
	s_and_saveexec_b64 s[8:9], s[30:31]
	s_cbranch_execz .LBB0_844
	v_ashrrev_i32_e32 v65, 31, v64
	s_waitcnt lgkmcnt(0)
	v_add_f32_e32 v68, v151, v66
	v_lshl_add_u64 v[66:67], v[64:65], 2, s[36:37]
	global_store_dword v[66:67], v68, off
	s_add_u32 s98, s98, 1
